# tool-generated LDS read pipelining (counted lgkmcnt, renamed buffers) in ma_ret loop and mc_item<2> j-loops
# speedup vs baseline: 1.0019x; 1.0000x over previous
; #define LAS __attribute__((address_space(3)))
; __device__ __forceinline__ f32x4 mma16(bf16x8 a, bf16x8 b, f32x4 c) { return __builtin_amdgcn_mfma_f32_16x16x32_bf16(a, b, c, 0, 0, 0); }
; template <int F> __device__ __forceinline__ void st_T(ldsp dst, int dp_unused, const u32x4 (&r)[F / 64], int wave, int lane) {
;     ldsp base = dst + (size_t)((2 * (wave >> 1) + (lane >> 5)) * 8 * 72 + 32 * (wave & 1) + (lane & 31)) * 2;
; #pragma unroll
;     for (int it = 0; it < F / 64; ++it) { const u32x4 w = r[it];
; #pragma unroll
;         for (int i = 0; i < 4; ++i) {
;             *(LAS bf16_t*)(base + (64 * it + 2 * i) * 144) = (bf16_t)(w[i] & 0xffffu);
;             *(LAS bf16_t*)(base + (64 * it + 2 * i + 1) * 144) = (bf16_t)(w[i] >> 16); } }
; }
; __device__ __forceinline__ void ma_ret_item(const Params& p, ldsp lds, int item) {
;     ...
;     for (int j = 0; j < 4; ++j) { const size_t rowj = (size_t)b * 2048 + (sc * 4 + j) * 64;
;         st_T<256>(KTt, 72, kr, wave, lane); st_T<128>(VTt, 72, vr, wave, lane);
;         __syncthreads();
;         if (j < 3) { const size_t rown = rowj + 64; ld_T<256>(kr, Pb + rown * NO + O_K + h * 256, NO, wave, lane); ld_T<128>(vr, Pb + rown * NO + O_V + h * 512 + es * 128, NO, wave, lane); }
; #pragma unroll
;         for (int ks = 0; ks < 2; ++ks) { const bf16x8 bf = ldfrag(VTt, (16 * wave + l15) * 72 + 32 * ks + 8 * q4);
; #pragma unroll
;             for (int i = 0; i < 16; ++i) acc[i] = mma16(ldfrag(KTt, (16 * i + l15) * 72 + 32 * ks + 8 * q4), bf, acc[i]); }
;         __syncthreads(); }
.LBB0_678:
	s_waitcnt vmcnt(5)
	ds_write_b16 v100, v22
	ds_write_b16_d16_hi v100, v22 offset:144
	ds_write_b16 v100, v23 offset:288
	ds_write_b16_d16_hi v100, v23 offset:432
	ds_write_b16 v100, v24 offset:576
	ds_write_b16_d16_hi v100, v24 offset:720
	ds_write_b16 v100, v25 offset:864
	ds_write_b16_d16_hi v100, v25 offset:1008
	s_waitcnt vmcnt(4)
	ds_write_b16 v100, v18 offset:9216
	ds_write_b16_d16_hi v100, v18 offset:9360
	ds_write_b16 v100, v19 offset:9504
	ds_write_b16_d16_hi v100, v19 offset:9648
	ds_write_b16 v100, v20 offset:9792
	ds_write_b16_d16_hi v100, v20 offset:9936
	ds_write_b16 v100, v21 offset:10080
	ds_write_b16_d16_hi v100, v21 offset:10224
	s_waitcnt vmcnt(3)
	ds_write_b16 v100, v12 offset:18432
	ds_write_b16_d16_hi v100, v12 offset:18576
	ds_write_b16 v100, v13 offset:18720
	ds_write_b16_d16_hi v100, v13 offset:18864
	ds_write_b16 v100, v14 offset:19008
	ds_write_b16_d16_hi v100, v14 offset:19152
	ds_write_b16 v100, v15 offset:19296
	ds_write_b16_d16_hi v100, v15 offset:19440
	s_waitcnt vmcnt(2)
	ds_write_b16 v100, v4 offset:27648
	ds_write_b16_d16_hi v100, v4 offset:27792
	ds_write_b16 v100, v5 offset:27936
	ds_write_b16_d16_hi v100, v5 offset:28080
	ds_write_b16 v100, v6 offset:28224
	ds_write_b16_d16_hi v100, v6 offset:28368
	ds_write_b16 v100, v7 offset:28512
	ds_write_b16_d16_hi v100, v7 offset:28656
	s_waitcnt vmcnt(1)
	ds_write_b16 v100, v8 offset:36864
	ds_write_b16_d16_hi v100, v8 offset:37008
	ds_write_b16 v100, v9 offset:37152
	ds_write_b16_d16_hi v100, v9 offset:37296
	ds_write_b16 v100, v10 offset:37440
	ds_write_b16_d16_hi v100, v10 offset:37584
	ds_write_b16 v100, v11 offset:37728
	ds_write_b16_d16_hi v100, v11 offset:37872
	s_waitcnt vmcnt(0)
	ds_write_b16 v100, v0 offset:46080
	ds_write_b16_d16_hi v100, v0 offset:46224
	ds_write_b16 v100, v1 offset:46368
	ds_write_b16_d16_hi v100, v1 offset:46512
	ds_write_b16 v100, v2 offset:46656
	ds_write_b16_d16_hi v100, v2 offset:46800
	ds_write_b16 v100, v3 offset:46944
	ds_write_b16_d16_hi v100, v3 offset:47088
	v_lshl_add_u64 v[0:1], v[98:99], 0, s[10:11]
	s_waitcnt lgkmcnt(0)
	s_barrier
	ds_read_b128 v[186:189], v130 offset:36864
	ds_read_b128 v[190:193], v132
	ds_read_b128 v[194:197], v131
	ds_read_b128 v[206:209], v129
	ds_read_b128 v[218:221], v128
	ds_read_b128 v[222:225], v127
	ds_read_b128 v[226:229], v126
	ds_read_b128 v[230:233], v125
	ds_read_b128 v[234:237], v124
	ds_read_b128 v[238:241], v123
	ds_read_b128 v[242:245], v122
	ds_read_b128 v[246:249], v121
	global_load_dwordx4 v[22:25], v[0:1], off offset:-256
	global_load_dwordx4 v[18:21], v[0:1], off offset:-128
	global_load_dwordx4 v[12:15], v[0:1], off
	global_load_dwordx4 v[4:7], v[0:1], off offset:128
	v_lshl_add_u64 v[0:1], v[96:97], 0, s[10:11]
	v_add_co_u32_e32 v0, vcc, s54, v0
	s_add_u32 s10, s10, 0xc0000
	s_nop 0
	v_addc_co_u32_e32 v1, vcc, 0, v1, vcc
	global_load_dwordx4 v[8:11], v[0:1], off
	s_nop 0
	global_load_dwordx4 v[0:3], v[0:1], off offset:128
	s_nop 2
	s_waitcnt lgkmcnt(10)
	v_mfma_f32_16x16x32_bf16 v[26:29], v[190:193], v[186:189], v[26:29]
	ds_read_b128 v[190:193], v120
	s_nop 0
	s_addc_u32 s11, s11, 0
	s_cmp_lg_u32 s10, 0x240000
	s_nop 0
	s_waitcnt lgkmcnt(10)
	v_mfma_f32_16x16x32_bf16 v[34:37], v[194:197], v[186:189], v[34:37]
	ds_read_b128 v[194:197], v119
	s_nop 1
	s_waitcnt lgkmcnt(10)
	v_mfma_f32_16x16x32_bf16 v[38:41], v[206:209], v[186:189], v[38:41]
	ds_read_b128 v[206:209], v118
	s_nop 1
	s_waitcnt lgkmcnt(10)
	v_mfma_f32_16x16x32_bf16 v[42:45], v[218:221], v[186:189], v[42:45]
	ds_read_b128 v[218:221], v117
	s_nop 1
	s_waitcnt lgkmcnt(10)
	v_mfma_f32_16x16x32_bf16 v[46:49], v[222:225], v[186:189], v[46:49]
	ds_read_b128 v[222:225], v116
	s_nop 1
	s_waitcnt lgkmcnt(10)
	v_mfma_f32_16x16x32_bf16 v[50:53], v[226:229], v[186:189], v[50:53]
	ds_read_b128 v[226:229], v130 offset:36928
	s_nop 1
	s_waitcnt lgkmcnt(10)
	v_mfma_f32_16x16x32_bf16 v[54:57], v[230:233], v[186:189], v[54:57]
	ds_read_b128 v[230:233], v115
	s_nop 1
	s_waitcnt lgkmcnt(10)
	v_mfma_f32_16x16x32_bf16 v[58:61], v[234:237], v[186:189], v[58:61]
	ds_read_b128 v[234:237], v114
	s_nop 1
	s_waitcnt lgkmcnt(10)
	v_mfma_f32_16x16x32_bf16 v[62:65], v[238:241], v[186:189], v[62:65]
	ds_read_b128 v[238:241], v113
	s_nop 1
	s_waitcnt lgkmcnt(10)
	v_mfma_f32_16x16x32_bf16 v[66:69], v[242:245], v[186:189], v[66:69]
	ds_read_b128 v[242:245], v112
	s_nop 1
	s_waitcnt lgkmcnt(10)
	v_mfma_f32_16x16x32_bf16 v[70:73], v[246:249], v[186:189], v[70:73]
	ds_read_b128 v[246:249], v111
	s_nop 1
	s_waitcnt lgkmcnt(10)
	v_mfma_f32_16x16x32_bf16 v[74:77], v[190:193], v[186:189], v[74:77]
	ds_read_b128 v[190:193], v110
	s_nop 1
	s_waitcnt lgkmcnt(10)
	v_mfma_f32_16x16x32_bf16 v[78:81], v[194:197], v[186:189], v[78:81]
	ds_read_b128 v[194:197], v109
	s_nop 1
	s_waitcnt lgkmcnt(10)
	v_mfma_f32_16x16x32_bf16 v[82:85], v[206:209], v[186:189], v[82:85]
	ds_read_b128 v[206:209], v108
	s_nop 1
	s_waitcnt lgkmcnt(10)
	v_mfma_f32_16x16x32_bf16 v[86:89], v[218:221], v[186:189], v[86:89]
	ds_read_b128 v[218:221], v107
	s_nop 1
	s_waitcnt lgkmcnt(10)
	v_mfma_f32_16x16x32_bf16 v[30:33], v[222:225], v[186:189], v[30:33]
	ds_read_b128 v[186:189], v106
	ds_read_b128 v[222:225], v105
	s_nop 2
	s_waitcnt lgkmcnt(10)
	v_mfma_f32_16x16x32_bf16 v[26:29], v[230:233], v[226:229], v[26:29]
	ds_read_b128 v[230:233], v104
	s_nop 1
	s_waitcnt lgkmcnt(10)
	v_mfma_f32_16x16x32_bf16 v[34:37], v[234:237], v[226:229], v[34:37]
	ds_read_b128 v[234:237], v103
	s_nop 1
	s_waitcnt lgkmcnt(10)
	v_mfma_f32_16x16x32_bf16 v[38:41], v[238:241], v[226:229], v[38:41]
	ds_read_b128 v[238:241], v102
	s_nop 1
	s_waitcnt lgkmcnt(10)
	v_mfma_f32_16x16x32_bf16 v[42:45], v[242:245], v[226:229], v[42:45]
	ds_read_b128 v[242:245], v101
	s_nop 1
	s_waitcnt lgkmcnt(10)
	v_mfma_f32_16x16x32_bf16 v[46:49], v[246:249], v[226:229], v[46:49]
	ds_read_b128 v[246:249], v16
	s_nop 1
	s_waitcnt lgkmcnt(10)
	v_mfma_f32_16x16x32_bf16 v[50:53], v[190:193], v[226:229], v[50:53]
	s_nop 1
	s_waitcnt lgkmcnt(9)
	v_mfma_f32_16x16x32_bf16 v[54:57], v[194:197], v[226:229], v[54:57]
	s_nop 1
	s_waitcnt lgkmcnt(8)
	v_mfma_f32_16x16x32_bf16 v[58:61], v[206:209], v[226:229], v[58:61]
	s_nop 1
	s_waitcnt lgkmcnt(7)
	v_mfma_f32_16x16x32_bf16 v[62:65], v[218:221], v[226:229], v[62:65]
	s_nop 1
	s_waitcnt lgkmcnt(6)
	v_mfma_f32_16x16x32_bf16 v[66:69], v[186:189], v[226:229], v[66:69]
	s_nop 1
	s_waitcnt lgkmcnt(5)
	v_mfma_f32_16x16x32_bf16 v[70:73], v[222:225], v[226:229], v[70:73]
	s_nop 1
	s_waitcnt lgkmcnt(4)
	v_mfma_f32_16x16x32_bf16 v[74:77], v[230:233], v[226:229], v[74:77]
	s_nop 1
	s_waitcnt lgkmcnt(3)
	v_mfma_f32_16x16x32_bf16 v[78:81], v[234:237], v[226:229], v[78:81]
	s_nop 1
	s_waitcnt lgkmcnt(2)
	v_mfma_f32_16x16x32_bf16 v[82:85], v[238:241], v[226:229], v[82:85]
	s_nop 1
	s_waitcnt lgkmcnt(1)
	v_mfma_f32_16x16x32_bf16 v[86:89], v[242:245], v[226:229], v[86:89]
	s_nop 1
	s_waitcnt lgkmcnt(0)
	s_barrier
; __device__ __forceinline__ f32x4 mma16(bf16x8 a, bf16x8 b, f32x4 c) { return __builtin_amdgcn_mfma_f32_16x16x32_bf16(a, b, c, 0, 0, 0); }
; __device__ __forceinline__ void ma_ret_item(const Params& p, ldsp lds, int item) {
;     ...
;     for (int j = 0; j < 4; ++j) { const size_t rowj = (size_t)b * 2048 + (sc * 4 + j) * 64;
;         st_T<256>(KTt, 72, kr, wave, lane); st_T<128>(VTt, 72, vr, wave, lane);
;         __syncthreads();
;         if (j < 3) { const size_t rown = rowj + 64; ld_T<256>(kr, Pb + rown * NO + O_K + h * 256, NO, wave, lane); ld_T<128>(vr, Pb + rown * NO + O_V + h * 512 + es * 128, NO, wave, lane); }
; #pragma unroll
;         for (int ks = 0; ks < 2; ++ks) { const bf16x8 bf = ldfrag(VTt, (16 * wave + l15) * 72 + 32 * ks + 8 * q4);
; #pragma unroll
;             for (int i = 0; i < 16; ++i) acc[i] = mma16(ldfrag(KTt, (16 * i + l15) * 72 + 32 * ks + 8 * q4), bf, acc[i]); }
;         __syncthreads(); }
	v_mfma_f32_16x16x32_bf16 v[30:33], v[246:249], v[226:229], v[30:33]
	v_mov_b32_e32 v90, v226
	v_mov_b32_e32 v91, v227
	v_mov_b32_e32 v92, v228
	v_mov_b32_e32 v93, v229
	v_mov_b32_e32 v137, v249
	s_cbranch_scc1 .LBB0_678
	s_waitcnt vmcnt(5)
	ds_write_b16 v100, v22
	ds_write_b16_d16_hi v100, v22 offset:144
	ds_write_b16 v100, v23 offset:288
	ds_write_b16_d16_hi v100, v23 offset:432
	ds_write_b16 v100, v24 offset:576
	ds_write_b16_d16_hi v100, v24 offset:720
	ds_write_b16 v100, v25 offset:864
	ds_write_b16_d16_hi v100, v25 offset:1008
	s_waitcnt vmcnt(4)
	ds_write_b16 v100, v18 offset:9216
	ds_write_b16_d16_hi v100, v18 offset:9360
	ds_write_b16 v100, v19 offset:9504
	ds_write_b16_d16_hi v100, v19 offset:9648
	ds_write_b16 v100, v20 offset:9792
	ds_write_b16_d16_hi v100, v20 offset:9936
	ds_write_b16 v100, v21 offset:10080
	ds_write_b16_d16_hi v100, v21 offset:10224
	s_waitcnt vmcnt(3)
	ds_write_b16 v100, v12 offset:18432
	ds_write_b16_d16_hi v100, v12 offset:18576
	ds_write_b16 v100, v13 offset:18720
	ds_write_b16_d16_hi v100, v13 offset:18864
	ds_write_b16 v100, v14 offset:19008
	ds_write_b16_d16_hi v100, v14 offset:19152
	ds_write_b16 v100, v15 offset:19296
	ds_write_b16_d16_hi v100, v15 offset:19440
	s_waitcnt vmcnt(2)
	ds_write_b16 v100, v4 offset:27648
	ds_write_b16_d16_hi v100, v4 offset:27792
	ds_write_b16 v100, v5 offset:27936
	ds_write_b16_d16_hi v100, v5 offset:28080
	ds_write_b16 v100, v6 offset:28224
	ds_write_b16_d16_hi v100, v6 offset:28368
	ds_write_b16 v100, v7 offset:28512
	ds_write_b16_d16_hi v100, v7 offset:28656
	s_waitcnt vmcnt(1)
	ds_write_b16 v100, v8 offset:36864
	ds_write_b16_d16_hi v100, v8 offset:37008
	ds_write_b16 v100, v9 offset:37152
	ds_write_b16_d16_hi v100, v9 offset:37296
	ds_write_b16 v100, v10 offset:37440
	ds_write_b16_d16_hi v100, v10 offset:37584
	ds_write_b16 v100, v11 offset:37728
	ds_write_b16_d16_hi v100, v11 offset:37872
	s_waitcnt vmcnt(0)
	ds_write_b16 v100, v0 offset:46080
	ds_write_b16_d16_hi v100, v0 offset:46224
	ds_write_b16 v100, v1 offset:46368
	ds_write_b16_d16_hi v100, v1 offset:46512
	ds_write_b16 v100, v2 offset:46656
	ds_write_b16_d16_hi v100, v2 offset:46800
	ds_write_b16 v100, v3 offset:46944
	ds_write_b16_d16_hi v100, v3 offset:47088
	s_waitcnt lgkmcnt(0)
	s_barrier
	ds_read_b128 v[0:3], v132
	ds_read_b128 v[4:7], v130 offset:36864
	ds_read_b128 v[8:11], v131
	ds_read_b128 v[12:15], v130 offset:36928
	ds_read_b128 v[18:21], v129
	ds_read_b128 v[22:25], v128
	s_waitcnt lgkmcnt(4)
	v_mfma_f32_16x16x32_bf16 v[0:3], v[0:3], v[4:7], v[26:29]
	s_ashr_i32 s1, s0, 31
	v_readlane_b32 s10, v255, 9
	s_lshl_b64 s[0:1], s[0:1], 12
	s_waitcnt lgkmcnt(3)
	v_mfma_f32_16x16x32_bf16 v[8:11], v[8:11], v[4:7], v[34:37]
	ds_read_b128 v[26:29], v127
	v_readlane_b32 s11, v255, 10
	s_or_b64 s[0:1], s[0:1], s[10:11]
	s_waitcnt lgkmcnt(2)
	v_mfma_f32_16x16x32_bf16 v[18:21], v[18:21], v[4:7], v[38:41]
	ds_read_b128 v[34:37], v126
	s_ashr_i32 s9, s8, 31
	s_add_i32 s12, s12, 1
	s_waitcnt lgkmcnt(2)
	v_mfma_f32_16x16x32_bf16 v[22:25], v[22:25], v[4:7], v[42:45]
	ds_read_b128 v[38:41], v125
	s_cmp_eq_u32 s12, 4
	s_nop 0
	ds_read_b128 v[42:45], v124
	s_waitcnt lgkmcnt(3)
	v_mfma_f32_16x16x32_bf16 v[26:29], v[26:29], v[4:7], v[46:49]
	s_waitcnt lgkmcnt(2)
	v_mfma_f32_16x16x32_bf16 v[34:37], v[34:37], v[4:7], v[50:53]
	s_nop 0
	ds_read_b128 v[46:49], v123
	s_nop 0
	ds_read_b128 v[50:53], v122
	s_waitcnt lgkmcnt(3)
	v_mfma_f32_16x16x32_bf16 v[38:41], v[38:41], v[4:7], v[54:57]
	s_waitcnt lgkmcnt(2)
	v_mfma_f32_16x16x32_bf16 v[42:45], v[42:45], v[4:7], v[58:61]
	s_nop 0
	ds_read_b128 v[54:57], v121
	s_nop 0
	ds_read_b128 v[58:61], v120
	s_waitcnt lgkmcnt(3)
	v_mfma_f32_16x16x32_bf16 v[46:49], v[46:49], v[4:7], v[62:65]
	s_waitcnt lgkmcnt(2)
	v_mfma_f32_16x16x32_bf16 v[50:53], v[50:53], v[4:7], v[66:69]
	s_nop 0
	ds_read_b128 v[62:65], v119
	s_nop 0
	ds_read_b128 v[66:69], v118
	s_waitcnt lgkmcnt(3)
	v_mfma_f32_16x16x32_bf16 v[54:57], v[54:57], v[4:7], v[70:73]
	s_waitcnt lgkmcnt(2)
	v_mfma_f32_16x16x32_bf16 v[58:61], v[58:61], v[4:7], v[74:77]
	s_nop 0
	ds_read_b128 v[70:73], v117
	s_nop 0
	ds_read_b128 v[74:77], v116
	s_waitcnt lgkmcnt(3)
	v_mfma_f32_16x16x32_bf16 v[62:65], v[62:65], v[4:7], v[78:81]
	s_waitcnt lgkmcnt(2)
	v_mfma_f32_16x16x32_bf16 v[66:69], v[66:69], v[4:7], v[82:85]
	s_nop 0
	ds_read_b128 v[78:81], v115
	s_waitcnt lgkmcnt(2)
	v_mfma_f32_16x16x32_bf16 v[70:73], v[70:73], v[4:7], v[86:89]
	s_waitcnt lgkmcnt(1)
	v_mfma_f32_16x16x32_bf16 v[4:7], v[74:77], v[4:7], v[30:33]
	ds_read_b128 v[74:77], v113
	s_nop 1
	ds_read_b128 v[30:33], v114
	s_waitcnt lgkmcnt(0)
	v_mfma_f32_16x16x32_bf16 v[8:11], v[30:33], v[12:15], v[8:11]
	ds_read_b128 v[30:33], v112
	v_mfma_f32_16x16x32_bf16 v[18:21], v[74:77], v[12:15], v[18:21]
	ds_read_b128 v[74:77], v111
	s_waitcnt lgkmcnt(1)
	v_mfma_f32_16x16x32_bf16 v[22:25], v[30:33], v[12:15], v[22:25]
	ds_read_b128 v[30:33], v110
	s_waitcnt lgkmcnt(1)
	v_mfma_f32_16x16x32_bf16 v[26:29], v[74:77], v[12:15], v[26:29]
	ds_read_b128 v[74:77], v109
	s_waitcnt lgkmcnt(1)
	v_mfma_f32_16x16x32_bf16 v[30:33], v[30:33], v[12:15], v[34:37]
	s_nop 2
	ds_read_b128 v[34:37], v108
	s_waitcnt lgkmcnt(1)
	v_mfma_f32_16x16x32_bf16 v[38:41], v[74:77], v[12:15], v[38:41]
	ds_read_b128 v[74:77], v107
	s_waitcnt lgkmcnt(1)
	v_mfma_f32_16x16x32_bf16 v[34:37], v[34:37], v[12:15], v[42:45]
	s_nop 2
	ds_read_b128 v[42:45], v106
	s_waitcnt lgkmcnt(1)
	v_mfma_f32_16x16x32_bf16 v[46:49], v[74:77], v[12:15], v[46:49]
	ds_read_b128 v[74:77], v105
	s_waitcnt lgkmcnt(1)
	v_mfma_f32_16x16x32_bf16 v[42:45], v[42:45], v[12:15], v[50:53]
	s_nop 2
	ds_read_b128 v[50:53], v104
	v_mfma_f32_16x16x32_bf16 v[0:3], v[78:81], v[12:15], v[0:3]
	s_waitcnt lgkmcnt(1)
	v_mfma_f32_16x16x32_bf16 v[54:57], v[74:77], v[12:15], v[54:57]
	ds_read_b128 v[74:77], v103
	ds_read_b128 v[78:81], v102
	s_waitcnt lgkmcnt(2)
	v_mfma_f32_16x16x32_bf16 v[50:53], v[50:53], v[12:15], v[58:61]
	s_nop 2
	ds_read_b128 v[58:61], v101
	ds_read_b128 v[82:85], v16
	s_waitcnt lgkmcnt(0)
	s_barrier
; __device__ __forceinline__ unsigned pk2(float lo, float hi) { return pg8::cvt_pk_bf16(lo, hi); }
; __device__ __forceinline__ f32x4 mma16(bf16x8 a, bf16x8 b, f32x4 c) { return __builtin_amdgcn_mfma_f32_16x16x32_bf16(a, b, c, 0, 0, 0); }
; __device__ __forceinline__ void ma_ret_item(const Params& p, ldsp lds, int item) {
;     ...
;         for (int ks = 0; ks < 2; ++ks) { const bf16x8 bf = ldfrag(VTt, (16 * wave + l15) * 72 + 32 * ks + 8 * q4);
; #pragma unroll
;             for (int i = 0; i < 16; ++i) acc[i] = mma16(ldfrag(KTt, (16 * i + l15) * 72 + 32 * ks + 8 * q4), bf, acc[i]); }
;         __syncthreads(); }
;     bf16_t* HL = (bf16_t*)(p.ws + WS_HL) + (((size_t)bh * 8 + sc) * 512 + es * 128 + 16 * wave + l15) * 256;
; #pragma unroll
;     for (int i = 0; i < 16; ++i) { u32x2 w; w.x = pk2(acc[i][0], acc[i][1]); w.y = pk2(acc[i][2], acc[i][3]); *(u32x2*)(HL + 16 * i + 4 * q4) = w; }
	v_mfma_f32_16x16x32_bf16 v[58:61], v[58:61], v[12:15], v[70:73]
	v_cvt_pk_bf16_f32 v0, v0, v1
	v_cvt_pk_bf16_f32 v1, v2, v3
	v_mfma_f32_16x16x32_bf16 v[62:65], v[74:77], v[12:15], v[62:65]
	s_nop 1
	v_or_b32_e32 v70, s0, v95
	v_mov_b32_e32 v71, s1
	v_lshl_add_u64 v[70:71], v[70:71], 0, s[8:9]
	v_readlane_b32 s0, v253, 34
	v_mfma_f32_16x16x32_bf16 v[66:69], v[78:81], v[12:15], v[66:69]
	v_readlane_b32 s1, v253, 35
	v_mov_b32_e32 v95, v17
	v_mfma_f32_16x16x32_bf16 v[4:7], v[82:85], v[12:15], v[4:7]
	v_lshlrev_b64 v[12:13], 9, v[70:71]
	v_lshl_add_u64 v[12:13], s[0:1], 0, v[12:13]
	v_lshl_add_u64 v[12:13], v[12:13], 0, v[94:95]
	global_store_dwordx2 v[12:13], v[0:1], off
	v_cvt_pk_bf16_f32 v0, v8, v9
	v_cvt_pk_bf16_f32 v1, v10, v11
	global_store_dwordx2 v[12:13], v[0:1], off offset:32
	v_cvt_pk_bf16_f32 v0, v18, v19
	v_cvt_pk_bf16_f32 v1, v20, v21
	global_store_dwordx2 v[12:13], v[0:1], off offset:64
	v_cvt_pk_bf16_f32 v0, v22, v23
	v_cvt_pk_bf16_f32 v1, v24, v25
	global_store_dwordx2 v[12:13], v[0:1], off offset:96
	v_cvt_pk_bf16_f32 v0, v26, v27
	v_cvt_pk_bf16_f32 v1, v28, v29
	global_store_dwordx2 v[12:13], v[0:1], off offset:128
	v_cvt_pk_bf16_f32 v0, v30, v31
	v_cvt_pk_bf16_f32 v1, v32, v33
	global_store_dwordx2 v[12:13], v[0:1], off offset:160
	v_cvt_pk_bf16_f32 v0, v38, v39
	v_cvt_pk_bf16_f32 v1, v40, v41
	global_store_dwordx2 v[12:13], v[0:1], off offset:192
	v_cvt_pk_bf16_f32 v0, v34, v35
	v_cvt_pk_bf16_f32 v1, v36, v37
	global_store_dwordx2 v[12:13], v[0:1], off offset:224
	v_cvt_pk_bf16_f32 v0, v46, v47
	v_cvt_pk_bf16_f32 v1, v48, v49
	global_store_dwordx2 v[12:13], v[0:1], off offset:256
	v_cvt_pk_bf16_f32 v0, v42, v43
	v_cvt_pk_bf16_f32 v1, v44, v45
	global_store_dwordx2 v[12:13], v[0:1], off offset:288
	v_cvt_pk_bf16_f32 v0, v54, v55
	v_cvt_pk_bf16_f32 v1, v56, v57
	global_store_dwordx2 v[12:13], v[0:1], off offset:320
	v_cvt_pk_bf16_f32 v0, v50, v51
	v_cvt_pk_bf16_f32 v1, v52, v53
	global_store_dwordx2 v[12:13], v[0:1], off offset:352
	v_cvt_pk_bf16_f32 v0, v62, v63
	v_cvt_pk_bf16_f32 v1, v64, v65
	global_store_dwordx2 v[12:13], v[0:1], off offset:384
	v_cvt_pk_bf16_f32 v0, v66, v67
	v_cvt_pk_bf16_f32 v1, v68, v69
	global_store_dwordx2 v[12:13], v[0:1], off offset:416
	v_cvt_pk_bf16_f32 v0, v58, v59
	v_cvt_pk_bf16_f32 v1, v60, v61
	global_store_dwordx2 v[12:13], v[0:1], off offset:448
	v_cvt_pk_bf16_f32 v0, v4, v5
	v_cvt_pk_bf16_f32 v1, v6, v7
	global_store_dwordx2 v[12:13], v[0:1], off offset:480
	s_cbranch_scc0 .LBB0_677

; #define LAS __attribute__((address_space(3)))
; template <int F> __device__ __forceinline__ void st_rows(ldsp dst, int dp, const u32x4 (&r)[(64 * (F / 8)) / NTHREADS], int tid) {
;     constexpr int G8 = F / 8;
; #pragma unroll
;     for (int it = 0; it < (64 * G8) / NTHREADS; ++it) { const int idx = tid + it * NTHREADS; const int s = idx / G8, g = idx % G8; *(LAS u32x4*)(dst + (size_t)(s * dp + g * 8) * 2) = r[it]; }
; }
; template <int F> __device__ __forceinline__ void ld_T(u32x4 (&r)[F / 64], const bf16_t* src, size_t sp, int wave, int lane) {
;     const bf16_t* base = src + (size_t)(32 * (wave & 1) + (lane & 31)) * sp + (2 * (wave >> 1) + (lane >> 5)) * 8;
; #pragma unroll
; template <int TY> __device__ __forceinline__ void mc_item(const Params& p, ldsp lds, int item) {
;     ...
;     for (int j = 0; j <= jc; ++j) { const size_t rowj = (size_t)b * 2048 + (sc * NB + j) * 64;
;         if constexpr (TY == 2) { st_rows<256>(KTs, PQ, kr, tid); st_T<512>(VTs, 72, vr, wave, lane); }
;         else { stage_rows<DK>(KTs, PQ, (const bf16_t*)(p.ws + WS_KT) + rowj * 768 + ecol, 768, tid);
;                stage_T<DV>(VTs, 72, Pb + rowj * PP + voff, PP, wave, lane); }
;         if constexpr (TY == 2) { __syncthreads(); if (j < jc) { const size_t rown = rowj + 64; ld_rows<256>(kr, Pb + rown * NO + O_K + h * 256, NO, tid); ld_T<512>(vr, Pb + rown * NO + voff, NO, wave, lane); } }
;         else BSYNC();
;         { f32x4 c0 = (f32x4){0.f, 0.f, 0.f, 0.f}, c1 = c0;
; #pragma unroll
;           for (int ks = 0; ks < DK / 32; ++ks) { const bf16x8 bq = ldfrag(QX, (16 * tt + l15) * PQ + 32 * ks + 8 * q4);
;               c0 = mma16(ldfrag(KTs, (16 * (2 * sp) + l15) * PQ + 32 * ks + 8 * q4), bq, c0);
;               c1 = mma16(ldfrag(KTs, (16 * (2 * sp + 1) + l15) * PQ + 32 * ks + 8 * q4), bq, c1); }
;           const int t = 16 * tt + l15;
;           const int tl = (j == jc) ? t : 4096;
; #pragma unroll
;           for (int jj = 0; jj < 4; ++jj) { if (32 * sp + 4 * q4 + jj > tl) c0[jj] = 0.f; if (32 * sp + 16 + 4 * q4 + jj > tl) c1[jj] = 0.f; }
;           u32x2 w; w.x = pk2(c0[0], c0[1]); w.y = pk2(c0[2], c0[3]); *(LAS u32x2*)(Pm + (size_t)(t * 72 + 32 * sp + 4 * q4) * 2) = w;
;           w.x = pk2(c1[0], c1[1]); w.y = pk2(c1[2], c1[3]); *(LAS u32x2*)(Pm + (size_t)(t * 72 + 32 * sp + 16 + 4 * q4) * 2) = w; }
;         if constexpr (TY == 2) __syncthreads(); else BSYNC();
.LBB0_859:
	v_add_u32_e32 v16, v211, v208
	s_waitcnt vmcnt(11)
	ds_write_b128 v16, v[130:133] offset:33792
	v_add_u32_e32 v16, v212, v209
	s_waitcnt vmcnt(10)
	ds_write_b128 v16, v[126:129] offset:33792
	v_add_u32_e32 v16, v213, v210
	s_waitcnt vmcnt(9)
	ds_write_b128 v16, v[122:125] offset:33792
	v_add_u32_e32 v16, v215, v214
	s_waitcnt vmcnt(8)
	ds_write_b128 v16, v[118:121] offset:33792
	s_waitcnt vmcnt(7)
	ds_write_b16 v206, v30
	ds_write_b16_d16_hi v206, v30 offset:144
	ds_write_b16 v206, v31 offset:288
	ds_write_b16_d16_hi v206, v31 offset:432
	ds_write_b16 v206, v32 offset:576
	ds_write_b16_d16_hi v206, v32 offset:720
	ds_write_b16 v206, v33 offset:864
	ds_write_b16_d16_hi v206, v33 offset:1008
	s_waitcnt vmcnt(6)
	ds_write_b16 v206, v22 offset:9216
	ds_write_b16_d16_hi v206, v22 offset:9360
	ds_write_b16 v206, v23 offset:9504
	ds_write_b16_d16_hi v206, v23 offset:9648
	ds_write_b16 v206, v24 offset:9792
	ds_write_b16_d16_hi v206, v24 offset:9936
	ds_write_b16 v206, v25 offset:10080
	ds_write_b16_d16_hi v206, v25 offset:10224
	s_waitcnt vmcnt(5)
	ds_write_b16 v206, v18 offset:18432
	ds_write_b16_d16_hi v206, v18 offset:18576
	ds_write_b16 v206, v19 offset:18720
	ds_write_b16_d16_hi v206, v19 offset:18864
	ds_write_b16 v206, v20 offset:19008
	ds_write_b16_d16_hi v206, v20 offset:19152
	ds_write_b16 v206, v21 offset:19296
	ds_write_b16_d16_hi v206, v21 offset:19440
	s_waitcnt vmcnt(4)
	ds_write_b16 v206, v12 offset:27648
	ds_write_b16_d16_hi v206, v12 offset:27792
	ds_write_b16 v206, v13 offset:27936
	ds_write_b16_d16_hi v206, v13 offset:28080
	ds_write_b16 v206, v14 offset:28224
	ds_write_b16_d16_hi v206, v14 offset:28368
	ds_write_b16 v206, v15 offset:28512
	ds_write_b16_d16_hi v206, v15 offset:28656
	s_waitcnt vmcnt(3)
	ds_write_b16 v206, v8 offset:36864
	ds_write_b16_d16_hi v206, v8 offset:37008
	ds_write_b16 v206, v9 offset:37152
	ds_write_b16_d16_hi v206, v9 offset:37296
	ds_write_b16 v206, v10 offset:37440
	ds_write_b16_d16_hi v206, v10 offset:37584
	ds_write_b16 v206, v11 offset:37728
	ds_write_b16_d16_hi v206, v11 offset:37872
	s_waitcnt vmcnt(2)
	ds_write_b16 v206, v4 offset:46080
	ds_write_b16_d16_hi v206, v4 offset:46224
	ds_write_b16 v206, v5 offset:46368
	ds_write_b16_d16_hi v206, v5 offset:46512
	ds_write_b16 v206, v6 offset:46656
	ds_write_b16_d16_hi v206, v6 offset:46800
	ds_write_b16 v206, v7 offset:46944
	ds_write_b16_d16_hi v206, v7 offset:47088
	s_waitcnt vmcnt(1)
	ds_write_b16 v206, v0 offset:55296
	ds_write_b16_d16_hi v206, v0 offset:55440
	ds_write_b16 v206, v1 offset:55584
	ds_write_b16_d16_hi v206, v1 offset:55728
	ds_write_b16 v206, v2 offset:55872
	ds_write_b16_d16_hi v206, v2 offset:56016
	ds_write_b16 v206, v3 offset:56160
	ds_write_b16_d16_hi v206, v3 offset:56304
	s_waitcnt vmcnt(0)
	ds_write_b16 v206, v114 offset:64512
	ds_write_b16_d16_hi v206, v114 offset:64656
	ds_write_b16 v206, v115 offset:64800
	ds_write_b16_d16_hi v206, v115 offset:64944
	ds_write_b16 v206, v116 offset:65088
	ds_write_b16_d16_hi v206, v116 offset:65232
	ds_write_b16 v206, v117 offset:65376
	ds_write_b16_d16_hi v206, v117 offset:65520
	v_lshl_add_u64 v[0:1], v[140:141], 0, s[38:39]
	s_waitcnt lgkmcnt(0)
	s_barrier
	global_load_dwordx4 v[130:133], v[0:1], off
	v_lshl_add_u64 v[0:1], v[142:143], 0, s[38:39]
	global_load_dwordx4 v[126:129], v[0:1], off
	v_lshl_add_u64 v[0:1], v[144:145], 0, s[38:39]
	global_load_dwordx4 v[122:125], v[0:1], off
	v_lshl_add_u64 v[0:1], v[146:147], 0, s[38:39]
	v_lshl_add_u64 v[114:115], v[148:149], 0, s[38:39]
	v_add_u32_e32 v16, 0, v207
	ds_read_b128 v[178:181], v16
	v_add_u32_e32 v166, 0, v217
	ds_read_b128 v[186:189], v166 offset:33792
	v_add_u32_e32 v167, 0, v216
	ds_read_b128 v[190:193], v167 offset:33792
	ds_read_b128 v[194:197], v16 offset:64
	ds_read_b128 v[218:221], v166 offset:33856
	ds_read_b128 v[222:225], v167 offset:33856
	ds_read_b128 v[226:229], v16 offset:128
	ds_read_b128 v[230:233], v166 offset:33920
	ds_read_b128 v[234:237], v167 offset:33920
	ds_read_b128 v[238:241], v16 offset:192
	ds_read_b128 v[242:245], v166 offset:33984
	ds_read_b128 v[246:249], v167 offset:33984
	global_load_dwordx4 v[118:121], v[0:1], off
	global_load_dwordx4 v[30:33], v[114:115], off offset:-512
	global_load_dwordx4 v[22:25], v[114:115], off offset:-384
	global_load_dwordx4 v[18:21], v[114:115], off offset:-256
	global_load_dwordx4 v[12:15], v[114:115], off offset:-128
	global_load_dwordx4 v[8:11], v[114:115], off
	global_load_dwordx4 v[4:7], v[114:115], off offset:128
	global_load_dwordx4 v[0:3], v[114:115], off offset:256
	s_nop 0
	global_load_dwordx4 v[114:117], v[114:115], off offset:384
	s_nop 3
	s_waitcnt lgkmcnt(10)
	v_mfma_f32_16x16x32_bf16 v[172:175], v[186:189], v[178:181], 0
	ds_read_b128 v[186:189], v16 offset:256
	s_add_u32 s38, s38, 0xc0000
	s_addc_u32 s39, s39, 0
	s_cmp_eq_u32 s9, s38
	s_nop 0
	s_waitcnt lgkmcnt(10)
	v_mfma_f32_16x16x32_bf16 v[134:137], v[190:193], v[178:181], 0
	ds_read_b128 v[178:181], v166 offset:34048
	ds_read_b128 v[190:193], v167 offset:34048
	s_nop 2
	s_waitcnt lgkmcnt(10)
	v_mfma_f32_16x16x32_bf16 v[172:175], v[218:221], v[194:197], v[172:175]
	ds_read_b128 v[218:221], v16 offset:320
	s_nop 1
	s_waitcnt lgkmcnt(10)
	v_mfma_f32_16x16x32_bf16 v[134:137], v[222:225], v[194:197], v[134:137]
	ds_read_b128 v[194:197], v166 offset:34112
	ds_read_b128 v[222:225], v167 offset:34112
	s_nop 2
	s_waitcnt lgkmcnt(10)
; #define LAS __attribute__((address_space(3)))
; __device__ __forceinline__ unsigned pk2(float lo, float hi) { return pg8::cvt_pk_bf16(lo, hi); }
; __device__ __forceinline__ f32x4 mma16(bf16x8 a, bf16x8 b, f32x4 c) { return __builtin_amdgcn_mfma_f32_16x16x32_bf16(a, b, c, 0, 0, 0); }
; #define BSYNC() do { asm volatile("s_waitcnt vmcnt(0) lgkmcnt(0)" ::: "memory"); __syncthreads(); } while (0)
; template <int TY> __device__ __forceinline__ void mc_item(const Params& p, ldsp lds, int item) {
;     ...
;         { f32x4 c0 = (f32x4){0.f, 0.f, 0.f, 0.f}, c1 = c0;
; #pragma unroll
;           for (int ks = 0; ks < DK / 32; ++ks) { const bf16x8 bq = ldfrag(QX, (16 * tt + l15) * PQ + 32 * ks + 8 * q4);
;               c0 = mma16(ldfrag(KTs, (16 * (2 * sp) + l15) * PQ + 32 * ks + 8 * q4), bq, c0);
;               c1 = mma16(ldfrag(KTs, (16 * (2 * sp + 1) + l15) * PQ + 32 * ks + 8 * q4), bq, c1); }
;           const int t = 16 * tt + l15;
;           const int tl = (j == jc) ? t : 4096;
; #pragma unroll
;           for (int jj = 0; jj < 4; ++jj) { if (32 * sp + 4 * q4 + jj > tl) c0[jj] = 0.f; if (32 * sp + 16 + 4 * q4 + jj > tl) c1[jj] = 0.f; }
;           u32x2 w; w.x = pk2(c0[0], c0[1]); w.y = pk2(c0[2], c0[3]); *(LAS u32x2*)(Pm + (size_t)(t * 72 + 32 * sp + 4 * q4) * 2) = w;
;           w.x = pk2(c1[0], c1[1]); w.y = pk2(c1[2], c1[3]); *(LAS u32x2*)(Pm + (size_t)(t * 72 + 32 * sp + 16 + 4 * q4) * 2) = w; }
;         if constexpr (TY == 2) __syncthreads(); else BSYNC();
; #pragma unroll
;         for (int ks = 0; ks < 2; ++ks) { bf16x8 pb[4];
; #pragma unroll
;             for (int tk = 0; tk < 4; ++tk) pb[tk] = ldfrag(Pm, (16 * tk + l15) * 72 + 32 * ks + 8 * q4);
; #pragma unroll
;             for (int ei = 0; ei < ET; ++ei) { const bf16x8 va = ldfrag(VTs, (16 * (wave * ET + ei) + l15) * 72 + 32 * ks + 8 * q4);
; #pragma unroll
;                 for (int tk = 0; tk < 4; ++tk) acc[ei][tk] = mma16(va, pb[tk], acc[ei][tk]); } }
;         if constexpr (TY == 2) __syncthreads(); else BSYNC(); }
	v_mfma_f32_16x16x32_bf16 v[172:175], v[230:233], v[226:229], v[172:175]
	ds_read_b128 v[230:233], v16 offset:384
	s_nop 1
	s_waitcnt lgkmcnt(10)
	v_mfma_f32_16x16x32_bf16 v[134:137], v[234:237], v[226:229], v[134:137]
	ds_read_b128 v[226:229], v166 offset:34176
	ds_read_b128 v[234:237], v167 offset:34176
	s_nop 2
	s_waitcnt lgkmcnt(10)
	v_mfma_f32_16x16x32_bf16 v[172:175], v[242:245], v[238:241], v[172:175]
	ds_read_b128 v[242:245], v16 offset:448
	s_nop 1
	s_waitcnt lgkmcnt(10)
	v_mfma_f32_16x16x32_bf16 v[134:137], v[246:249], v[238:241], v[134:137]
	ds_read_b128 v[238:241], v166 offset:34240
	ds_read_b128 v[246:249], v167 offset:34240
	s_nop 2
	s_waitcnt lgkmcnt(10)
	v_mfma_f32_16x16x32_bf16 v[172:175], v[178:181], v[186:189], v[172:175]
	s_nop 1
	s_waitcnt lgkmcnt(9)
	v_mfma_f32_16x16x32_bf16 v[134:137], v[190:193], v[186:189], v[134:137]
	s_nop 2
	s_waitcnt lgkmcnt(7)
	v_mfma_f32_16x16x32_bf16 v[172:175], v[194:197], v[218:221], v[172:175]
	s_nop 1
	s_waitcnt lgkmcnt(6)
	v_mfma_f32_16x16x32_bf16 v[134:137], v[222:225], v[218:221], v[134:137]
	s_nop 2
	s_waitcnt lgkmcnt(4)
	v_mfma_f32_16x16x32_bf16 v[172:175], v[226:229], v[230:233], v[172:175]
	s_nop 1
	s_waitcnt lgkmcnt(3)
	v_mfma_f32_16x16x32_bf16 v[134:137], v[234:237], v[230:233], v[134:137]
	s_nop 1
	v_mov_b32_e32 v16, s41
	s_nop 0
	s_waitcnt lgkmcnt(1)
	v_mfma_f32_16x16x32_bf16 v[172:175], v[238:241], v[242:245], v[172:175]
	s_nop 1
	s_waitcnt lgkmcnt(0)
	v_mfma_f32_16x16x32_bf16 v[134:137], v[246:249], v[242:245], v[134:137]
	v_mov_b32_e32 v176, s41
	s_nop 3
	v_cndmask_b32_e64 v16, v172, v16, s[20:21]
	v_cndmask_b32_e64 v168, v175, 0, s[16:17]
	s_nop 0
	v_cndmask_b32_e32 v166, v134, v176, vcc
	v_cndmask_b32_e64 v134, v173, 0, s[10:11]
	v_cndmask_b32_e64 v167, v135, 0, s[12:13]
	v_cndmask_b32_e64 v135, v174, 0, s[10:11]
	v_cvt_pk_bf16_f32 v134, v16, v134
	v_add_u32_e32 v16, 0, v156
	v_cvt_pk_bf16_f32 v135, v135, v168
	v_add_u32_e32 v16, 0x22800, v16
	v_cndmask_b32_e64 v136, v136, 0, s[14:15]
	v_cndmask_b32_e64 v137, v137, 0, s[18:19]
	ds_write_b64 v16, v[134:135]
	v_cvt_pk_bf16_f32 v134, v166, v167
	v_cvt_pk_bf16_f32 v135, v136, v137
	ds_write_b64 v16, v[134:135] offset:32
	v_add_u32_e32 v16, v154, v163
	v_add_u32_e32 v166, v139, v162
	s_nop 0
	s_waitcnt lgkmcnt(0)
	s_barrier
	ds_read_b128 v[178:181], v16
	ds_read_b128 v[186:189], v16 offset:2304
	ds_read_b128 v[190:193], v16 offset:4608
	ds_read_b128 v[194:197], v16 offset:6912
	ds_read_b128 v[218:221], v166
	ds_read_b128 v[222:225], v166 offset:2304
	ds_read_b128 v[226:229], v166 offset:4608
	ds_read_b128 v[230:233], v166 offset:6912
	ds_read_b128 v[234:237], v16 offset:64
	ds_read_b128 v[238:241], v16 offset:2368
	ds_read_b128 v[242:245], v16 offset:4672
	ds_read_b128 v[246:249], v16 offset:6976
	s_nop 5
	s_waitcnt lgkmcnt(7)
	v_mfma_f32_16x16x32_bf16 v[42:45], v[218:221], v[178:181], v[42:45]
	v_mfma_f32_16x16x32_bf16 v[38:41], v[218:221], v[186:189], v[38:41]
	v_mfma_f32_16x16x32_bf16 v[34:37], v[218:221], v[190:193], v[34:37]
	v_mfma_f32_16x16x32_bf16 v[26:29], v[218:221], v[194:197], v[26:29]
	ds_read_b128 v[218:221], v166 offset:64
	s_nop 1
	s_waitcnt lgkmcnt(7)
	v_mfma_f32_16x16x32_bf16 v[46:49], v[222:225], v[178:181], v[46:49]
	v_mfma_f32_16x16x32_bf16 v[50:53], v[222:225], v[186:189], v[50:53]
	v_mfma_f32_16x16x32_bf16 v[54:57], v[222:225], v[190:193], v[54:57]
	v_mfma_f32_16x16x32_bf16 v[58:61], v[222:225], v[194:197], v[58:61]
	ds_read_b128 v[222:225], v166 offset:2368
	s_nop 1
	s_waitcnt lgkmcnt(7)
	v_mfma_f32_16x16x32_bf16 v[66:69], v[226:229], v[178:181], v[66:69]
	v_mfma_f32_16x16x32_bf16 v[70:73], v[226:229], v[186:189], v[70:73]
	v_mfma_f32_16x16x32_bf16 v[82:85], v[226:229], v[190:193], v[82:85]
	v_mfma_f32_16x16x32_bf16 v[86:89], v[226:229], v[194:197], v[86:89]
	ds_read_b128 v[226:229], v166 offset:4672
	s_nop 1
	s_waitcnt lgkmcnt(7)
	v_mfma_f32_16x16x32_bf16 v[98:101], v[230:233], v[178:181], v[98:101]
	ds_read_b128 v[178:181], v166 offset:6976
	v_mfma_f32_16x16x32_bf16 v[102:105], v[230:233], v[186:189], v[102:105]
	v_mfma_f32_16x16x32_bf16 v[106:109], v[230:233], v[190:193], v[106:109]
	v_mfma_f32_16x16x32_bf16 v[110:113], v[230:233], v[194:197], v[110:113]
	s_nop 5
	s_waitcnt lgkmcnt(3)
	v_mfma_f32_16x16x32_bf16 v[42:45], v[218:221], v[234:237], v[42:45]
	v_mfma_f32_16x16x32_bf16 v[38:41], v[218:221], v[238:241], v[38:41]
	v_mfma_f32_16x16x32_bf16 v[34:37], v[218:221], v[242:245], v[34:37]
	v_mfma_f32_16x16x32_bf16 v[26:29], v[218:221], v[246:249], v[26:29]
	s_nop 1
	s_waitcnt lgkmcnt(2)
	v_mfma_f32_16x16x32_bf16 v[46:49], v[222:225], v[234:237], v[46:49]
	v_mfma_f32_16x16x32_bf16 v[50:53], v[222:225], v[238:241], v[50:53]
	v_mfma_f32_16x16x32_bf16 v[54:57], v[222:225], v[242:245], v[54:57]
	v_mfma_f32_16x16x32_bf16 v[58:61], v[222:225], v[246:249], v[58:61]
	s_nop 1
	s_waitcnt lgkmcnt(1)
	v_mfma_f32_16x16x32_bf16 v[66:69], v[226:229], v[234:237], v[66:69]
	v_mfma_f32_16x16x32_bf16 v[70:73], v[226:229], v[238:241], v[70:73]
	v_mfma_f32_16x16x32_bf16 v[82:85], v[226:229], v[242:245], v[82:85]
	v_mfma_f32_16x16x32_bf16 v[86:89], v[226:229], v[246:249], v[86:89]
	s_nop 1
	s_waitcnt lgkmcnt(0)
	s_barrier
	v_mfma_f32_16x16x32_bf16 v[98:101], v[178:181], v[234:237], v[98:101]
	v_mfma_f32_16x16x32_bf16 v[102:105], v[178:181], v[238:241], v[102:105]
	v_mfma_f32_16x16x32_bf16 v[106:109], v[178:181], v[242:245], v[106:109]
	v_mfma_f32_16x16x32_bf16 v[110:113], v[178:181], v[246:249], v[110:113]
	s_cbranch_scc0 .LBB0_859
	s_movk_i32 s9, 0x90
	s_branch .LBB0_862

; #define LAS __attribute__((address_space(3)))
; template <int F> __device__ __forceinline__ void st_rows(ldsp dst, int dp, const u32x4 (&r)[(64 * (F / 8)) / NTHREADS], int tid) {
;     constexpr int G8 = F / 8;
; #pragma unroll
;     for (int it = 0; it < (64 * G8) / NTHREADS; ++it) { const int idx = tid + it * NTHREADS; const int s = idx / G8, g = idx % G8; *(LAS u32x4*)(dst + (size_t)(s * dp + g * 8) * 2) = r[it]; }
; }
; template <int F> __device__ __forceinline__ void ld_T(u32x4 (&r)[F / 64], const bf16_t* src, size_t sp, int wave, int lane) {
;     const bf16_t* base = src + (size_t)(32 * (wave & 1) + (lane & 31)) * sp + (2 * (wave >> 1) + (lane >> 5)) * 8;
; #pragma unroll
; template <int TY> __device__ __forceinline__ void mc_item(const Params& p, ldsp lds, int item) {
;     ...
;     for (int j = 0; j <= jc; ++j) { const size_t rowj = (size_t)b * 2048 + (sc * NB + j) * 64;
;         if constexpr (TY == 2) { st_rows<256>(KTs, PQ, kr, tid); st_T<512>(VTs, 72, vr, wave, lane); }
;         else { stage_rows<DK>(KTs, PQ, (const bf16_t*)(p.ws + WS_KT) + rowj * 768 + ecol, 768, tid);
;                stage_T<DV>(VTs, 72, Pb + rowj * PP + voff, PP, wave, lane); }
;         if constexpr (TY == 2) { __syncthreads(); if (j < jc) { const size_t rown = rowj + 64; ld_rows<256>(kr, Pb + rown * NO + O_K + h * 256, NO, tid); ld_T<512>(vr, Pb + rown * NO + voff, NO, wave, lane); } }
;         else BSYNC();
;         { f32x4 c0 = (f32x4){0.f, 0.f, 0.f, 0.f}, c1 = c0;
; #pragma unroll
;           for (int ks = 0; ks < DK / 32; ++ks) { const bf16x8 bq = ldfrag(QX, (16 * tt + l15) * PQ + 32 * ks + 8 * q4);
;               c0 = mma16(ldfrag(KTs, (16 * (2 * sp) + l15) * PQ + 32 * ks + 8 * q4), bq, c0);
;               c1 = mma16(ldfrag(KTs, (16 * (2 * sp + 1) + l15) * PQ + 32 * ks + 8 * q4), bq, c1); }
;           const int t = 16 * tt + l15;
;           const int tl = (j == jc) ? t : 4096;
; #pragma unroll
;           for (int jj = 0; jj < 4; ++jj) { if (32 * sp + 4 * q4 + jj > tl) c0[jj] = 0.f; if (32 * sp + 16 + 4 * q4 + jj > tl) c1[jj] = 0.f; }
;           u32x2 w; w.x = pk2(c0[0], c0[1]); w.y = pk2(c0[2], c0[3]); *(LAS u32x2*)(Pm + (size_t)(t * 72 + 32 * sp + 4 * q4) * 2) = w;
;           w.x = pk2(c1[0], c1[1]); w.y = pk2(c1[2], c1[3]); *(LAS u32x2*)(Pm + (size_t)(t * 72 + 32 * sp + 16 + 4 * q4) * 2) = w; }
;         if constexpr (TY == 2) __syncthreads(); else BSYNC();
.LBB0_880:
	v_add_u32_e32 v16, v206, v203
	s_waitcnt vmcnt(11)
	ds_write_b128 v16, v[130:133] offset:33792
	v_add_u32_e32 v16, v207, v204
	s_waitcnt vmcnt(10)
	ds_write_b128 v16, v[126:129] offset:33792
	v_add_u32_e32 v16, v208, v205
	s_waitcnt vmcnt(9)
	ds_write_b128 v16, v[122:125] offset:33792
	v_add_u32_e32 v16, v210, v209
	s_waitcnt vmcnt(8)
	ds_write_b128 v16, v[118:121] offset:33792
	s_waitcnt vmcnt(7)
	ds_write_b16 v162, v26
	ds_write_b16_d16_hi v162, v26 offset:144
	ds_write_b16 v162, v27 offset:288
	ds_write_b16_d16_hi v162, v27 offset:432
	ds_write_b16 v162, v28 offset:576
	ds_write_b16_d16_hi v162, v28 offset:720
	ds_write_b16 v162, v29 offset:864
	ds_write_b16_d16_hi v162, v29 offset:1008
	s_waitcnt vmcnt(6)
	ds_write_b16 v162, v22 offset:9216
	ds_write_b16_d16_hi v162, v22 offset:9360
	ds_write_b16 v162, v23 offset:9504
	ds_write_b16_d16_hi v162, v23 offset:9648
	ds_write_b16 v162, v24 offset:9792
	ds_write_b16_d16_hi v162, v24 offset:9936
	ds_write_b16 v162, v25 offset:10080
	ds_write_b16_d16_hi v162, v25 offset:10224
	s_waitcnt vmcnt(5)
	ds_write_b16 v162, v18 offset:18432
	ds_write_b16_d16_hi v162, v18 offset:18576
	ds_write_b16 v162, v19 offset:18720
	ds_write_b16_d16_hi v162, v19 offset:18864
	ds_write_b16 v162, v20 offset:19008
	ds_write_b16_d16_hi v162, v20 offset:19152
	ds_write_b16 v162, v21 offset:19296
	ds_write_b16_d16_hi v162, v21 offset:19440
	s_waitcnt vmcnt(4)
	ds_write_b16 v162, v12 offset:27648
	ds_write_b16_d16_hi v162, v12 offset:27792
	ds_write_b16 v162, v13 offset:27936
	ds_write_b16_d16_hi v162, v13 offset:28080
	ds_write_b16 v162, v14 offset:28224
	ds_write_b16_d16_hi v162, v14 offset:28368
	ds_write_b16 v162, v15 offset:28512
	ds_write_b16_d16_hi v162, v15 offset:28656
	s_waitcnt vmcnt(3)
	ds_write_b16 v162, v8 offset:36864
	ds_write_b16_d16_hi v162, v8 offset:37008
	ds_write_b16 v162, v9 offset:37152
	ds_write_b16_d16_hi v162, v9 offset:37296
	ds_write_b16 v162, v10 offset:37440
	ds_write_b16_d16_hi v162, v10 offset:37584
	ds_write_b16 v162, v11 offset:37728
	ds_write_b16_d16_hi v162, v11 offset:37872
	s_waitcnt vmcnt(2)
	ds_write_b16 v162, v4 offset:46080
	ds_write_b16_d16_hi v162, v4 offset:46224
	ds_write_b16 v162, v5 offset:46368
	ds_write_b16_d16_hi v162, v5 offset:46512
	ds_write_b16 v162, v6 offset:46656
	ds_write_b16_d16_hi v162, v6 offset:46800
	ds_write_b16 v162, v7 offset:46944
	ds_write_b16_d16_hi v162, v7 offset:47088
	s_waitcnt vmcnt(1)
	ds_write_b16 v162, v0 offset:55296
	ds_write_b16_d16_hi v162, v0 offset:55440
	ds_write_b16 v162, v1 offset:55584
	ds_write_b16_d16_hi v162, v1 offset:55728
	ds_write_b16 v162, v2 offset:55872
	ds_write_b16_d16_hi v162, v2 offset:56016
	ds_write_b16 v162, v3 offset:56160
	ds_write_b16_d16_hi v162, v3 offset:56304
	s_waitcnt vmcnt(0)
	ds_write_b16 v162, v98 offset:64512
	ds_write_b16_d16_hi v162, v98 offset:64656
	ds_write_b16 v162, v99 offset:64800
	ds_write_b16_d16_hi v162, v99 offset:64944
	ds_write_b16 v162, v100 offset:65088
	ds_write_b16_d16_hi v162, v100 offset:65232
	ds_write_b16 v162, v101 offset:65376
	ds_write_b16_d16_hi v162, v101 offset:65520
	v_lshl_add_u64 v[0:1], v[140:141], 0, s[38:39]
	s_waitcnt lgkmcnt(0)
	s_barrier
	global_load_dwordx4 v[130:133], v[0:1], off
	v_lshl_add_u64 v[0:1], v[142:143], 0, s[38:39]
	global_load_dwordx4 v[126:129], v[0:1], off
	v_lshl_add_u64 v[0:1], v[144:145], 0, s[38:39]
	global_load_dwordx4 v[122:125], v[0:1], off
	v_lshl_add_u64 v[0:1], v[146:147], 0, s[38:39]
	v_lshl_add_u64 v[98:99], v[148:149], 0, s[38:39]
	v_add_u32_e32 v16, 0, v163
	ds_read_b128 v[178:181], v16
	v_add_u32_e32 v166, 0, v217
	ds_read_b128 v[186:189], v166 offset:33792
	v_add_u32_e32 v167, 0, v216
	ds_read_b128 v[190:193], v167 offset:33792
	ds_read_b128 v[194:197], v16 offset:64
	ds_read_b128 v[218:221], v166 offset:33856
	ds_read_b128 v[222:225], v167 offset:33856
	ds_read_b128 v[226:229], v16 offset:128
	ds_read_b128 v[230:233], v166 offset:33920
	ds_read_b128 v[234:237], v167 offset:33920
	ds_read_b128 v[238:241], v16 offset:192
	ds_read_b128 v[242:245], v166 offset:33984
	ds_read_b128 v[246:249], v167 offset:33984
	global_load_dwordx4 v[118:121], v[0:1], off
	global_load_dwordx4 v[26:29], v[98:99], off offset:-512
	global_load_dwordx4 v[22:25], v[98:99], off offset:-384
	global_load_dwordx4 v[18:21], v[98:99], off offset:-256
	global_load_dwordx4 v[12:15], v[98:99], off offset:-128
	global_load_dwordx4 v[8:11], v[98:99], off
	global_load_dwordx4 v[4:7], v[98:99], off offset:128
	global_load_dwordx4 v[0:3], v[98:99], off offset:256
	s_nop 0
	global_load_dwordx4 v[98:101], v[98:99], off offset:384
	s_nop 3
	s_waitcnt lgkmcnt(10)
	v_mfma_f32_16x16x32_bf16 v[172:175], v[186:189], v[178:181], 0
	ds_read_b128 v[186:189], v16 offset:256
	s_add_u32 s38, s38, 0xc0000
	s_addc_u32 s39, s39, 0
	s_cmp_eq_u32 s9, s38
	s_nop 0
	s_waitcnt lgkmcnt(10)
	v_mfma_f32_16x16x32_bf16 v[134:137], v[190:193], v[178:181], 0
	ds_read_b128 v[178:181], v166 offset:34048
	ds_read_b128 v[190:193], v167 offset:34048
	s_nop 2
	s_waitcnt lgkmcnt(10)
	v_mfma_f32_16x16x32_bf16 v[172:175], v[218:221], v[194:197], v[172:175]
	ds_read_b128 v[218:221], v16 offset:320
	s_nop 1
	s_waitcnt lgkmcnt(10)
	v_mfma_f32_16x16x32_bf16 v[134:137], v[222:225], v[194:197], v[134:137]
	ds_read_b128 v[194:197], v166 offset:34112
	ds_read_b128 v[222:225], v167 offset:34112
	s_nop 2
	s_waitcnt lgkmcnt(10)
; #define LAS __attribute__((address_space(3)))
; __device__ __forceinline__ unsigned pk2(float lo, float hi) { return pg8::cvt_pk_bf16(lo, hi); }
; __device__ __forceinline__ f32x4 mma16(bf16x8 a, bf16x8 b, f32x4 c) { return __builtin_amdgcn_mfma_f32_16x16x32_bf16(a, b, c, 0, 0, 0); }
; #define BSYNC() do { asm volatile("s_waitcnt vmcnt(0) lgkmcnt(0)" ::: "memory"); __syncthreads(); } while (0)
; template <int TY> __device__ __forceinline__ void mc_item(const Params& p, ldsp lds, int item) {
;     ...
;         { f32x4 c0 = (f32x4){0.f, 0.f, 0.f, 0.f}, c1 = c0;
; #pragma unroll
;           for (int ks = 0; ks < DK / 32; ++ks) { const bf16x8 bq = ldfrag(QX, (16 * tt + l15) * PQ + 32 * ks + 8 * q4);
;               c0 = mma16(ldfrag(KTs, (16 * (2 * sp) + l15) * PQ + 32 * ks + 8 * q4), bq, c0);
;               c1 = mma16(ldfrag(KTs, (16 * (2 * sp + 1) + l15) * PQ + 32 * ks + 8 * q4), bq, c1); }
;           const int t = 16 * tt + l15;
;           const int tl = (j == jc) ? t : 4096;
; #pragma unroll
;           for (int jj = 0; jj < 4; ++jj) { if (32 * sp + 4 * q4 + jj > tl) c0[jj] = 0.f; if (32 * sp + 16 + 4 * q4 + jj > tl) c1[jj] = 0.f; }
;           u32x2 w; w.x = pk2(c0[0], c0[1]); w.y = pk2(c0[2], c0[3]); *(LAS u32x2*)(Pm + (size_t)(t * 72 + 32 * sp + 4 * q4) * 2) = w;
;           w.x = pk2(c1[0], c1[1]); w.y = pk2(c1[2], c1[3]); *(LAS u32x2*)(Pm + (size_t)(t * 72 + 32 * sp + 16 + 4 * q4) * 2) = w; }
;         if constexpr (TY == 2) __syncthreads(); else BSYNC();
; #pragma unroll
;         for (int ks = 0; ks < 2; ++ks) { bf16x8 pb[4];
; #pragma unroll
;             for (int tk = 0; tk < 4; ++tk) pb[tk] = ldfrag(Pm, (16 * tk + l15) * 72 + 32 * ks + 8 * q4);
; #pragma unroll
;             for (int ei = 0; ei < ET; ++ei) { const bf16x8 va = ldfrag(VTs, (16 * (wave * ET + ei) + l15) * 72 + 32 * ks + 8 * q4);
; #pragma unroll
;                 for (int tk = 0; tk < 4; ++tk) acc[ei][tk] = mma16(va, pb[tk], acc[ei][tk]); } }
;         if constexpr (TY == 2) __syncthreads(); else BSYNC(); }
	v_mfma_f32_16x16x32_bf16 v[172:175], v[230:233], v[226:229], v[172:175]
	ds_read_b128 v[230:233], v16 offset:384
	s_nop 1
	s_waitcnt lgkmcnt(10)
	v_mfma_f32_16x16x32_bf16 v[134:137], v[234:237], v[226:229], v[134:137]
	ds_read_b128 v[226:229], v166 offset:34176
	ds_read_b128 v[234:237], v167 offset:34176
	s_nop 2
	s_waitcnt lgkmcnt(10)
	v_mfma_f32_16x16x32_bf16 v[172:175], v[242:245], v[238:241], v[172:175]
	ds_read_b128 v[242:245], v16 offset:448
	s_nop 1
	s_waitcnt lgkmcnt(10)
	v_mfma_f32_16x16x32_bf16 v[134:137], v[246:249], v[238:241], v[134:137]
	ds_read_b128 v[238:241], v166 offset:34240
	ds_read_b128 v[246:249], v167 offset:34240
	s_nop 2
	s_waitcnt lgkmcnt(10)
	v_mfma_f32_16x16x32_bf16 v[172:175], v[178:181], v[186:189], v[172:175]
	s_nop 1
	s_waitcnt lgkmcnt(9)
	v_mfma_f32_16x16x32_bf16 v[134:137], v[190:193], v[186:189], v[134:137]
	s_nop 2
	s_waitcnt lgkmcnt(7)
	v_mfma_f32_16x16x32_bf16 v[172:175], v[194:197], v[218:221], v[172:175]
	s_nop 1
	s_waitcnt lgkmcnt(6)
	v_mfma_f32_16x16x32_bf16 v[134:137], v[222:225], v[218:221], v[134:137]
	s_nop 2
	s_waitcnt lgkmcnt(4)
	v_mfma_f32_16x16x32_bf16 v[172:175], v[226:229], v[230:233], v[172:175]
	s_nop 1
	s_waitcnt lgkmcnt(3)
	v_mfma_f32_16x16x32_bf16 v[134:137], v[234:237], v[230:233], v[134:137]
	s_nop 1
	v_mov_b32_e32 v16, s41
	s_nop 0
	s_waitcnt lgkmcnt(1)
	v_mfma_f32_16x16x32_bf16 v[172:175], v[238:241], v[242:245], v[172:175]
	s_nop 1
	s_waitcnt lgkmcnt(0)
	v_mfma_f32_16x16x32_bf16 v[134:137], v[246:249], v[242:245], v[134:137]
	v_mov_b32_e32 v176, s41
	s_nop 3
	v_cndmask_b32_e64 v16, v172, v16, s[20:21]
	v_cndmask_b32_e64 v168, v175, 0, s[16:17]
	s_nop 0
	v_cndmask_b32_e32 v166, v134, v176, vcc
	v_cndmask_b32_e64 v134, v173, 0, s[10:11]
	v_cndmask_b32_e64 v167, v135, 0, s[12:13]
	v_cndmask_b32_e64 v135, v174, 0, s[10:11]
	v_cvt_pk_bf16_f32 v134, v16, v134
	v_add_u32_e32 v16, 0, v156
	v_cvt_pk_bf16_f32 v135, v135, v168
	v_add_u32_e32 v16, 0x22800, v16
	v_cndmask_b32_e64 v136, v136, 0, s[14:15]
	v_cndmask_b32_e64 v137, v137, 0, s[18:19]
	ds_write_b64 v16, v[134:135]
	v_cvt_pk_bf16_f32 v134, v166, v167
	v_cvt_pk_bf16_f32 v135, v136, v137
	ds_write_b64 v16, v[134:135] offset:32
	v_add_u32_e32 v16, v154, v201
	v_add_u32_e32 v166, v139, v202
	s_nop 0
	s_waitcnt lgkmcnt(0)
	s_barrier
	ds_read_b128 v[178:181], v16
	ds_read_b128 v[186:189], v16 offset:2304
	ds_read_b128 v[190:193], v16 offset:4608
	ds_read_b128 v[194:197], v16 offset:6912
	ds_read_b128 v[218:221], v166
	ds_read_b128 v[222:225], v166 offset:2304
	ds_read_b128 v[226:229], v166 offset:4608
	ds_read_b128 v[230:233], v166 offset:6912
	ds_read_b128 v[234:237], v16 offset:64
	ds_read_b128 v[238:241], v16 offset:2368
	ds_read_b128 v[242:245], v16 offset:4672
	ds_read_b128 v[246:249], v16 offset:6976
	s_nop 5
	s_waitcnt lgkmcnt(7)
	v_mfma_f32_16x16x32_bf16 v[62:65], v[218:221], v[178:181], v[62:65]
	v_mfma_f32_16x16x32_bf16 v[58:61], v[218:221], v[186:189], v[58:61]
	v_mfma_f32_16x16x32_bf16 v[50:53], v[218:221], v[190:193], v[50:53]
	v_mfma_f32_16x16x32_bf16 v[42:45], v[218:221], v[194:197], v[42:45]
	ds_read_b128 v[218:221], v166 offset:64
	s_nop 1
	s_waitcnt lgkmcnt(7)
	v_mfma_f32_16x16x32_bf16 v[66:69], v[222:225], v[178:181], v[66:69]
	v_mfma_f32_16x16x32_bf16 v[70:73], v[222:225], v[186:189], v[70:73]
	v_mfma_f32_16x16x32_bf16 v[74:77], v[222:225], v[190:193], v[74:77]
	v_mfma_f32_16x16x32_bf16 v[78:81], v[222:225], v[194:197], v[78:81]
	ds_read_b128 v[222:225], v166 offset:2368
	s_nop 1
	s_waitcnt lgkmcnt(7)
	v_mfma_f32_16x16x32_bf16 v[82:85], v[226:229], v[178:181], v[82:85]
	v_mfma_f32_16x16x32_bf16 v[86:89], v[226:229], v[186:189], v[86:89]
	v_mfma_f32_16x16x32_bf16 v[90:93], v[226:229], v[190:193], v[90:93]
	v_mfma_f32_16x16x32_bf16 v[94:97], v[226:229], v[194:197], v[94:97]
	ds_read_b128 v[226:229], v166 offset:4672
	s_nop 1
	s_waitcnt lgkmcnt(7)
	v_mfma_f32_16x16x32_bf16 v[102:105], v[230:233], v[178:181], v[102:105]
	ds_read_b128 v[178:181], v166 offset:6976
	v_mfma_f32_16x16x32_bf16 v[106:109], v[230:233], v[186:189], v[106:109]
	v_mfma_f32_16x16x32_bf16 v[110:113], v[230:233], v[190:193], v[110:113]
	v_mfma_f32_16x16x32_bf16 v[114:117], v[230:233], v[194:197], v[114:117]
	s_nop 5
	s_waitcnt lgkmcnt(3)
	v_mfma_f32_16x16x32_bf16 v[62:65], v[218:221], v[234:237], v[62:65]
	v_mfma_f32_16x16x32_bf16 v[58:61], v[218:221], v[238:241], v[58:61]
	v_mfma_f32_16x16x32_bf16 v[50:53], v[218:221], v[242:245], v[50:53]
	v_mfma_f32_16x16x32_bf16 v[42:45], v[218:221], v[246:249], v[42:45]
	s_nop 1
	s_waitcnt lgkmcnt(2)
	v_mfma_f32_16x16x32_bf16 v[66:69], v[222:225], v[234:237], v[66:69]
	v_mfma_f32_16x16x32_bf16 v[70:73], v[222:225], v[238:241], v[70:73]
	v_mfma_f32_16x16x32_bf16 v[74:77], v[222:225], v[242:245], v[74:77]
	v_mfma_f32_16x16x32_bf16 v[78:81], v[222:225], v[246:249], v[78:81]
	s_nop 1
	s_waitcnt lgkmcnt(1)
	v_mfma_f32_16x16x32_bf16 v[82:85], v[226:229], v[234:237], v[82:85]
	v_mfma_f32_16x16x32_bf16 v[86:89], v[226:229], v[238:241], v[86:89]
	v_mfma_f32_16x16x32_bf16 v[90:93], v[226:229], v[242:245], v[90:93]
	v_mfma_f32_16x16x32_bf16 v[94:97], v[226:229], v[246:249], v[94:97]
	s_nop 1
	s_waitcnt lgkmcnt(0)
	s_barrier
	v_mfma_f32_16x16x32_bf16 v[102:105], v[178:181], v[234:237], v[102:105]
	v_mfma_f32_16x16x32_bf16 v[106:109], v[178:181], v[238:241], v[106:109]
	v_mfma_f32_16x16x32_bf16 v[110:113], v[178:181], v[242:245], v[110:113]
	v_mfma_f32_16x16x32_bf16 v[114:117], v[178:181], v[246:249], v[114:117]
	s_cbranch_scc0 .LBB0_880
	s_movk_i32 s9, 0x90
	s_branch .LBB0_883
